# phase 0: weight-transpose items rebalanced 6/18 per wave between GEMV and non-GEMV workgroups (was 7/15)
# speedup vs baseline: 1.0073x; 1.0073x over previous
.LBB0_30:
	s_ashr_i32 s13, s18, 6
	s_lshl_b32 s4, s2, 3
	s_add_i32 s16, s13, s4
	s_add_i32 s10, s16, 0x1e00
	s_and_b64 s[4:5], s[8:9], exec
	s_cselect_b32 s17, s16, s10
	s_cmpk_eq_i32 s66, 0x100
	s_cselect_b64 s[4:5], -1, 0
	s_and_b64 s[10:11], s[4:5], exec
	s_cselect_b32 s10, s17, s16
	s_and_b64 s[8:9], s[8:9], s[4:5]
	s_movk_i32 s11, 0x2400
	s_and_b64 s[8:9], s[8:9], exec
	s_cselect_b32 s11, s11, 0x4800
	s_cmp_ge_i32 s10, s11
	s_waitcnt lgkmcnt(0)
	s_barrier
	s_cbranch_scc1 .LBB0_43
	s_lshl_b32 s8, s66, 3
	s_and_b64 s[4:5], s[4:5], exec
	s_cselect_b32 s12, s12, s8
	s_lshl_b32 s4, s13, 14
	v_bfe_u32 v18, v21, 5, 1
	s_add_i32 s4, s4, 0
	v_and_b32_e32 v12, 0x7c, v19
	v_mul_u32_u24_e32 v0, 0x84, v18
	v_add3_u32 v19, s4, v12, v0
	v_lshlrev_b32_e32 v0, 3, v21
	v_bfe_u32 v20, v21, 3, 3
	v_and_b32_e32 v0, 56, v0
	v_mul_u32_u24_e32 v1, 0x84, v0
	v_lshlrev_b32_e32 v2, 2, v20
	v_add3_u32 v21, s4, v1, v2
	v_lshlrev_b32_e32 v0, 1, v0
	v_mov_b32_e32 v1, 0
	v_lshl_add_u64 v[2:3], s[6:7], 0, v[0:1]
	s_mov_b64 s[6:7], 0x5000000
	v_lshl_add_u64 v[4:5], v[2:3], 0, s[6:7]
	s_load_dwordx2 s[6:7], s[0:1], 0x48
	s_load_dwordx4 s[16:19], s[0:1], 0x68
	s_mov_b64 s[8:9], 0x4000000
	v_mov_b32_e32 v13, v1
	s_mov_b32 s5, 0
	v_or_b32_e32 v22, 8, v20
	v_or_b32_e32 v23, 16, v20
	v_or_b32_e32 v24, 24, v20
	v_lshl_add_u64 v[6:7], v[2:3], 0, s[8:9]
	s_waitcnt lgkmcnt(0)
	v_lshl_add_u64 v[8:9], s[18:19], 0, v[12:13]
	v_lshl_add_u64 v[10:11], s[16:17], 0, v[12:13]
	v_lshl_add_u64 v[12:13], s[6:7], 0, v[12:13]
	s_lshl_b32 s13, s10, 5
	s_lshl_b32 s16, s12, 5
	s_mov_b32 s17, 0x10000
	s_mov_b32 s18, 0x20000
	s_mov_b32 s19, 0x30000
	s_mov_b32 s20, 0x40000
	s_mov_b32 s21, 0x50000
	s_mov_b32 s22, 0x60000
	s_mov_b32 s23, 0x70000
	s_movk_i32 s24, 0xe400
	v_add_u32_e32 v25, 0x400, v19
	v_add_u32_e32 v26, 0x800, v19
	v_add_u32_e32 v27, 0xc00, v19
	v_add_u32_e32 v28, 0x1000, v19
	v_add_u32_e32 v29, 0x1400, v19
	v_add_u32_e32 v30, 0x1800, v19
	v_add_u32_e32 v31, 0x1c00, v19
	s_branch .LBB0_34
